# v054 + counted waits at unit boundaries (F1/F7): in a unit's first K-loop iteration the first two segment waits are vmcnt(18) instead of vmcnt(8), so the previous epilogue's stores and prefetch DMAs m
# speedup vs baseline: 1.0114x; 1.0053x over previous
.LBB0_311:
	s_mov_b32 s101, 0
	s_and_b32 s14, s13, 3
	s_add_i32 m0, s68, 0x18000
	v_lshl_add_u64 v[8:9], v[8:9], 0, s[44:45]
	s_lshl_b32 s15, s4, 6
	s_lshl_b32 s10, s4, 13
	s_lshl_b32 s11, s14, 12
	s_waitcnt vmcnt(2)
	s_barrier
	global_load_lds_dwordx4 v[8:9], off
	v_lshl_add_u64 v[6:7], v[6:7], 0, s[44:45]
	s_add_i32 m0, s68, 0x1a000
	s_add_i32 s72, s68, 0x8000
	s_add_i32 s73, s68, 0xa000
	global_load_lds_dwordx4 v[6:7], off
	v_lshl_add_u64 v[2:3], v[2:3], 0, s[44:45]
	s_mov_b32 m0, s72
	s_add_u32 s4, s26, 0x80080
	global_load_lds_dwordx4 v[2:3], off
	v_lshl_add_u64 v[2:3], v[4:5], 0, s[44:45]
	s_mov_b32 m0, s73
	s_addc_u32 s5, s27, 0
	global_load_lds_dwordx4 v[2:3], off
	s_add_i32 m0, s68, 0x1c000
	v_lshl_add_u64 v[2:3], s[4:5], 0, v[162:163]
	global_load_lds_dwordx4 v[2:3], off
	v_lshl_add_u64 v[2:3], s[4:5], 0, v[134:135]
	s_add_i32 m0, s68, 0x1e000
	v_lshrrev_b32_e32 v4, 1, v143
	global_load_lds_dwordx4 v[2:3], off
	s_and_b32 s4, s2, 7
	v_and_b32_e32 v159, 24, v4
	s_lshl_b32 s5, s4, 3
	s_ashr_i32 s75, s2, 6
	s_bfe_u32 s77, s2, 0x30003
	s_mul_i32 s4, s4, 44
	v_and_b32_e32 v3, 15, v143
	v_lshlrev_b32_e32 v4, 1, v159
	v_lshlrev_b32_e32 v5, 2, v143
	s_ashr_i32 s74, s2, 31
	s_add_i32 s76, s5, s75
	s_or_b32 s78, s5, s77
	s_lshr_b32 s79, s4, 3
	v_or_b32_e32 v2, s15, v3
	v_lshl_or_b32 v3, v3, 6, v4
	v_and_b32_e32 v5, 32, v5
	s_cmpk_lt_u32 s12, 0x100
	v_bitop3_b32 v6, v3, s10, v5 bitop3:0xde
	v_bitop3_b32 v161, v3, s11, v5 bitop3:0xde
	s_cselect_b64 s[10:11], -1, 0
	s_ashr_i32 s4, s15, 31
	v_mov_b32_e32 v3, s4
	s_lshl_b32 s4, s13, 6
	s_bfe_u32 s80, s13, 0x10001
	s_lshl_b32 s81, s14, 7
	s_and_b32 s4, s4, 64
	s_add_u32 s4, s56, s4
	s_addc_u32 s5, s57, 0
	v_mov_b32_e32 v5, v163
	v_lshlrev_b32_e32 v173, 3, v2
	v_lshl_add_u64 v[4:5], s[4:5], 0, v[4:5]
	v_lshlrev_b64 v[2:3], 7, v[2:3]
	v_lshl_add_u64 v[2:3], v[4:5], 0, v[2:3]
	s_mov_b64 s[4:5], 0x58000000
	v_lshl_add_u64 v[136:137], v[2:3], 0, s[4:5]
	v_lshlrev_b32_e32 v2, 14, v13
	v_and_b32_e32 v2, 0xffff8000, v2
	v_lshl_add_u32 v2, v14, 11, v2
	v_and_b32_e32 v3, 1, v13
	v_lshl_or_b32 v2, v3, 6, v2
	v_lshl_add_u32 v138, v15, 1, v2
	v_lshlrev_b32_e32 v2, 14, v10
	v_and_b32_e32 v2, 0xffff8000, v2
	s_waitcnt vmcnt(6)
	v_lshl_add_u32 v2, v11, 11, v2
	v_and_b32_e32 v3, 1, v10
	v_lshl_or_b32 v2, v3, 6, v2
	v_mov_b32_e32 v139, v163
	v_lshl_add_u32 v140, v12, 1, v2
	v_mov_b32_e32 v141, v163
	s_mov_b32 s83, 0
	v_add_u32_e32 v177, 0, v6
	s_mov_b32 s82, 0
	s_barrier
	s_branch .LBB0_314

.LBB0_323:
	s_add_u32 s26, s24, 0xfffc0080
	s_addc_u32 s27, s25, -1
	s_add_i32 s36, 0, 0x10000
	s_cmp_eq_u32 s21, 12
	s_cselect_b32 s57, s17, s27
	s_cselect_b32 s56, s16, s26
	v_add_u32_e32 v142, s36, v161
	s_cselect_b32 s27, s19, s15
	s_cselect_b32 s26, s18, s13
	s_add_i32 s38, 0, 0x14000
	ds_read_b128 v[144:147], v142
	ds_read_b128 v[148:151], v142 offset:1024
	ds_read_b128 v[152:155], v142 offset:2048
	ds_read_b128 v[178:181], v142 offset:3072
	v_add_u32_e32 v142, s38, v161
	ds_read_b128 v[182:185], v142
	ds_read_b128 v[186:189], v142 offset:1024
	ds_read_b128 v[190:193], v142 offset:2048
	ds_read_b128 v[194:197], v142 offset:3072
	v_lshl_add_u64 v[156:157], s[24:25], 0, v[140:141]
	s_add_i32 m0, s68, 0xc000
	ds_read_b128 v[198:201], v177
	ds_read_b128 v[202:205], v177 offset:1024
	ds_read_b128 v[206:209], v177 offset:2048
	ds_read_b128 v[210:213], v177 offset:3072
	ds_read_b128 v[214:217], v177 offset:4096
	ds_read_b128 v[222:225], v177 offset:5120
	ds_read_b128 v[226:229], v177 offset:6144
	ds_read_b128 v[230:233], v177 offset:7168
	global_load_lds_dwordx4 v[156:157], off
	v_lshl_add_u64 v[156:157], s[24:25], 0, v[138:139]
	s_add_i32 m0, s68, 0xe000
	s_nop 0
	global_load_lds_dwordx4 v[156:157], off
	s_waitcnt vmcnt(18)
	s_cmp_eq_i32 s21, -2
	s_cselect_b32 s100, s101, 0
	s_cmp_lg_u32 s100, 0
	s_cbranch_scc1 .Lrw_skip323_0
	s_waitcnt vmcnt(8)
.Lrw_skip323_0:
	s_waitcnt lgkmcnt(0)
	s_barrier
	v_mfma_i32_16x16x64_i8 v[126:129], v[144:147], v[198:201], v[126:129]
	v_mfma_i32_16x16x64_i8 v[118:121], v[152:155], v[198:201], v[118:121]
	v_mfma_i32_16x16x64_i8 v[110:113], v[144:147], v[206:209], v[110:113]
	v_mfma_i32_16x16x64_i8 v[102:105], v[152:155], v[206:209], v[102:105]
	v_mfma_i32_16x16x64_i8 v[94:97], v[144:147], v[214:217], v[94:97]
	v_mfma_i32_16x16x64_i8 v[86:89], v[152:155], v[214:217], v[86:89]
	v_mfma_i32_16x16x64_i8 v[78:81], v[144:147], v[226:229], v[78:81]
	v_mfma_i32_16x16x64_i8 v[70:73], v[152:155], v[226:229], v[70:73]
	v_mfma_i32_16x16x64_i8 v[126:129], v[148:151], v[202:205], v[126:129]
	v_mfma_i32_16x16x64_i8 v[118:121], v[178:181], v[202:205], v[118:121]
	v_mfma_i32_16x16x64_i8 v[110:113], v[148:151], v[210:213], v[110:113]
	v_mfma_i32_16x16x64_i8 v[102:105], v[178:181], v[210:213], v[102:105]
	v_mfma_i32_16x16x64_i8 v[94:97], v[148:151], v[222:225], v[94:97]
	v_mfma_i32_16x16x64_i8 v[86:89], v[178:181], v[222:225], v[86:89]
	v_mfma_i32_16x16x64_i8 v[78:81], v[148:151], v[230:233], v[78:81]
	v_mfma_i32_16x16x64_i8 v[70:73], v[178:181], v[230:233], v[70:73]
	v_mfma_i32_16x16x64_i8 v[122:125], v[182:185], v[198:201], v[122:125]
	v_mfma_i32_16x16x64_i8 v[114:117], v[190:193], v[198:201], v[114:117]
	v_mfma_i32_16x16x64_i8 v[106:109], v[182:185], v[206:209], v[106:109]
	v_mfma_i32_16x16x64_i8 v[98:101], v[190:193], v[206:209], v[98:101]
	v_mfma_i32_16x16x64_i8 v[90:93], v[182:185], v[214:217], v[90:93]
	v_mfma_i32_16x16x64_i8 v[82:85], v[190:193], v[214:217], v[82:85]
	v_mfma_i32_16x16x64_i8 v[74:77], v[182:185], v[226:229], v[74:77]
	v_mfma_i32_16x16x64_i8 v[66:69], v[190:193], v[226:229], v[66:69]
	v_mfma_i32_16x16x64_i8 v[122:125], v[186:189], v[202:205], v[122:125]
	v_mfma_i32_16x16x64_i8 v[114:117], v[194:197], v[202:205], v[114:117]
	v_mfma_i32_16x16x64_i8 v[106:109], v[186:189], v[210:213], v[106:109]
	v_mfma_i32_16x16x64_i8 v[98:101], v[194:197], v[210:213], v[98:101]
	v_mfma_i32_16x16x64_i8 v[90:93], v[186:189], v[222:225], v[90:93]
	v_mfma_i32_16x16x64_i8 v[82:85], v[194:197], v[222:225], v[82:85]
	v_mfma_i32_16x16x64_i8 v[74:77], v[186:189], v[230:233], v[74:77]
	v_mfma_i32_16x16x64_i8 v[66:69], v[194:197], v[230:233], v[66:69]
	s_barrier
	s_add_i32 s36, s36, s23
	v_lshl_add_u64 v[156:157], s[26:27], 0, v[162:163]
	s_mov_b32 m0, s36
	ds_read_b128 v[198:201], v177 offset:16384
	ds_read_b128 v[202:205], v177 offset:17408
	ds_read_b128 v[206:209], v177 offset:18432
	ds_read_b128 v[210:213], v177 offset:19456
	ds_read_b128 v[214:217], v177 offset:20480
	ds_read_b128 v[222:225], v177 offset:21504
	ds_read_b128 v[226:229], v177 offset:22528
	ds_read_b128 v[230:233], v177 offset:23552
	global_load_lds_dwordx4 v[156:157], off
	s_add_i32 m0, s36, 0x2000
	s_add_u32 s36, s26, 0x80000
	v_lshl_add_u64 v[174:175], s[26:27], 0, v[134:135]
	s_addc_u32 s37, s27, 0
	s_add_i32 s38, s38, s23
	global_load_lds_dwordx4 v[174:175], off
	v_lshl_add_u64 v[234:235], s[36:37], 0, v[162:163]
	s_mov_b32 m0, s38
	v_lshl_add_u64 v[236:237], s[56:57], 0, v[132:133]
	global_load_lds_dwordx4 v[234:235], off
	v_lshl_add_u64 v[234:235], s[36:37], 0, v[134:135]
	s_add_i32 m0, s38, 0x2000
	s_nop 0
	global_load_lds_dwordx4 v[234:235], off
	v_lshl_add_u64 v[234:235], s[56:57], 0, v[130:131]
	s_mov_b32 m0, s68
	s_nop 0
	global_load_lds_dwordx4 v[234:235], off
	s_mov_b32 m0, s69
	s_nop 0
	global_load_lds_dwordx4 v[236:237], off
	s_waitcnt vmcnt(18)
	s_cmp_eq_i32 s21, -2
	s_cselect_b32 s100, s101, 0
	s_cmp_lg_u32 s100, 0
	s_cbranch_scc1 .Lrw_skip323_1
	s_waitcnt vmcnt(8)
.Lrw_skip323_1:
	s_waitcnt lgkmcnt(0)
	s_barrier
	v_mfma_i32_16x16x64_i8 v[62:65], v[144:147], v[198:201], v[62:65]
	v_mfma_i32_16x16x64_i8 v[54:57], v[152:155], v[198:201], v[54:57]
	v_mfma_i32_16x16x64_i8 v[46:49], v[144:147], v[206:209], v[46:49]
	v_mfma_i32_16x16x64_i8 v[38:41], v[152:155], v[206:209], v[38:41]
	v_mfma_i32_16x16x64_i8 v[30:33], v[144:147], v[214:217], v[30:33]
	v_mfma_i32_16x16x64_i8 v[22:25], v[152:155], v[214:217], v[22:25]
	v_mfma_i32_16x16x64_i8 v[14:17], v[144:147], v[226:229], v[14:17]
	v_mfma_i32_16x16x64_i8 v[6:9], v[152:155], v[226:229], v[6:9]
	v_mfma_i32_16x16x64_i8 v[62:65], v[148:151], v[202:205], v[62:65]
	v_mfma_i32_16x16x64_i8 v[54:57], v[178:181], v[202:205], v[54:57]
	v_mfma_i32_16x16x64_i8 v[46:49], v[148:151], v[210:213], v[46:49]
	v_mfma_i32_16x16x64_i8 v[38:41], v[178:181], v[210:213], v[38:41]
	v_mfma_i32_16x16x64_i8 v[30:33], v[148:151], v[222:225], v[30:33]
	v_mfma_i32_16x16x64_i8 v[22:25], v[178:181], v[222:225], v[22:25]
	v_mfma_i32_16x16x64_i8 v[14:17], v[148:151], v[230:233], v[14:17]
	v_mfma_i32_16x16x64_i8 v[6:9], v[178:181], v[230:233], v[6:9]
	v_mfma_i32_16x16x64_i8 v[58:61], v[182:185], v[198:201], v[58:61]
	v_mfma_i32_16x16x64_i8 v[50:53], v[190:193], v[198:201], v[50:53]
	v_mfma_i32_16x16x64_i8 v[42:45], v[182:185], v[206:209], v[42:45]
	v_mfma_i32_16x16x64_i8 v[34:37], v[190:193], v[206:209], v[34:37]
	v_mfma_i32_16x16x64_i8 v[26:29], v[182:185], v[214:217], v[26:29]
	v_mfma_i32_16x16x64_i8 v[18:21], v[190:193], v[214:217], v[18:21]
	v_mfma_i32_16x16x64_i8 v[10:13], v[182:185], v[226:229], v[10:13]
	v_mfma_i32_16x16x64_i8 v[2:5], v[190:193], v[226:229], v[2:5]
	v_mfma_i32_16x16x64_i8 v[58:61], v[186:189], v[202:205], v[58:61]
	v_mfma_i32_16x16x64_i8 v[50:53], v[194:197], v[202:205], v[50:53]
	v_mfma_i32_16x16x64_i8 v[42:45], v[186:189], v[210:213], v[42:45]
	v_mfma_i32_16x16x64_i8 v[34:37], v[194:197], v[210:213], v[34:37]
	v_mfma_i32_16x16x64_i8 v[26:29], v[186:189], v[222:225], v[26:29]
	v_mfma_i32_16x16x64_i8 v[18:21], v[194:197], v[222:225], v[18:21]
	v_mfma_i32_16x16x64_i8 v[10:13], v[186:189], v[230:233], v[10:13]
	v_mfma_i32_16x16x64_i8 v[2:5], v[194:197], v[230:233], v[2:5]
	s_barrier
	s_add_i32 s38, 0, 0x18000
	v_add_u32_e32 v142, s38, v161
	s_add_i32 s39, 0, 0x1c000
	ds_read_b128 v[144:147], v142
	ds_read_b128 v[148:151], v142 offset:1024
	ds_read_b128 v[152:155], v142 offset:2048
	ds_read_b128 v[178:181], v142 offset:3072
	v_add_u32_e32 v142, s39, v161
	ds_read_b128 v[182:185], v142
	ds_read_b128 v[186:189], v142 offset:1024
	ds_read_b128 v[190:193], v142 offset:2048
	ds_read_b128 v[194:197], v142 offset:3072
	s_add_u32 s36, s56, 0x40000
	s_addc_u32 s37, s57, 0
	s_mov_b32 m0, s70
	v_lshl_add_u64 v[238:239], s[36:37], 0, v[130:131]
	ds_read_b128 v[198:201], v177 offset:32768
	ds_read_b128 v[202:205], v177 offset:33792
	ds_read_b128 v[206:209], v177 offset:34816
	ds_read_b128 v[210:213], v177 offset:35840
	ds_read_b128 v[214:217], v177 offset:36864
	ds_read_b128 v[222:225], v177 offset:37888
	ds_read_b128 v[226:229], v177 offset:38912
	ds_read_b128 v[230:233], v177 offset:39936
	global_load_lds_dwordx4 v[238:239], off
	v_lshl_add_u64 v[238:239], s[36:37], 0, v[132:133]
	s_mov_b32 m0, s71
	s_nop 0
	global_load_lds_dwordx4 v[238:239], off
	s_waitcnt vmcnt(8)
	s_waitcnt lgkmcnt(0)
	s_barrier
	v_mfma_i32_16x16x64_i8 v[126:129], v[144:147], v[198:201], v[126:129]
	v_mfma_i32_16x16x64_i8 v[118:121], v[152:155], v[198:201], v[118:121]
	v_mfma_i32_16x16x64_i8 v[110:113], v[144:147], v[206:209], v[110:113]
	v_mfma_i32_16x16x64_i8 v[102:105], v[152:155], v[206:209], v[102:105]
	v_mfma_i32_16x16x64_i8 v[94:97], v[144:147], v[214:217], v[94:97]
	v_mfma_i32_16x16x64_i8 v[86:89], v[152:155], v[214:217], v[86:89]
	v_mfma_i32_16x16x64_i8 v[78:81], v[144:147], v[226:229], v[78:81]
	v_mfma_i32_16x16x64_i8 v[70:73], v[152:155], v[226:229], v[70:73]
	v_mfma_i32_16x16x64_i8 v[126:129], v[148:151], v[202:205], v[126:129]
	v_mfma_i32_16x16x64_i8 v[118:121], v[178:181], v[202:205], v[118:121]
	v_mfma_i32_16x16x64_i8 v[110:113], v[148:151], v[210:213], v[110:113]
	v_mfma_i32_16x16x64_i8 v[102:105], v[178:181], v[210:213], v[102:105]
	v_mfma_i32_16x16x64_i8 v[94:97], v[148:151], v[222:225], v[94:97]
	v_mfma_i32_16x16x64_i8 v[86:89], v[178:181], v[222:225], v[86:89]
	v_mfma_i32_16x16x64_i8 v[78:81], v[148:151], v[230:233], v[78:81]
	v_mfma_i32_16x16x64_i8 v[70:73], v[178:181], v[230:233], v[70:73]
	v_mfma_i32_16x16x64_i8 v[122:125], v[182:185], v[198:201], v[122:125]
	v_mfma_i32_16x16x64_i8 v[114:117], v[190:193], v[198:201], v[114:117]
	v_mfma_i32_16x16x64_i8 v[106:109], v[182:185], v[206:209], v[106:109]
	v_mfma_i32_16x16x64_i8 v[98:101], v[190:193], v[206:209], v[98:101]
	v_mfma_i32_16x16x64_i8 v[90:93], v[182:185], v[214:217], v[90:93]
	v_mfma_i32_16x16x64_i8 v[82:85], v[190:193], v[214:217], v[82:85]
	v_mfma_i32_16x16x64_i8 v[74:77], v[182:185], v[226:229], v[74:77]
	v_mfma_i32_16x16x64_i8 v[66:69], v[190:193], v[226:229], v[66:69]
	v_mfma_i32_16x16x64_i8 v[122:125], v[186:189], v[202:205], v[122:125]
	v_mfma_i32_16x16x64_i8 v[114:117], v[194:197], v[202:205], v[114:117]
	v_mfma_i32_16x16x64_i8 v[106:109], v[186:189], v[210:213], v[106:109]
	v_mfma_i32_16x16x64_i8 v[98:101], v[194:197], v[210:213], v[98:101]
	v_mfma_i32_16x16x64_i8 v[90:93], v[186:189], v[222:225], v[90:93]
	v_mfma_i32_16x16x64_i8 v[82:85], v[194:197], v[222:225], v[82:85]
	v_mfma_i32_16x16x64_i8 v[74:77], v[186:189], v[230:233], v[74:77]
	v_mfma_i32_16x16x64_i8 v[66:69], v[194:197], v[230:233], v[66:69]
	s_barrier
	s_add_i32 s36, s38, s23
	v_lshl_add_u64 v[156:157], v[156:157], 0, s[44:45]
	s_mov_b32 m0, s36
	ds_read_b128 v[198:201], v177 offset:49152
	ds_read_b128 v[202:205], v177 offset:50176
	ds_read_b128 v[206:209], v177 offset:51200
	ds_read_b128 v[210:213], v177 offset:52224
	ds_read_b128 v[214:217], v177 offset:53248
	ds_read_b128 v[222:225], v177 offset:54272
	ds_read_b128 v[226:229], v177 offset:55296
	ds_read_b128 v[230:233], v177 offset:56320
	global_load_lds_dwordx4 v[156:157], off
	s_add_i32 m0, s36, 0x2000
	s_add_u32 s26, s26, 0x80080
	v_lshl_add_u64 v[156:157], v[174:175], 0, s[44:45]
	s_addc_u32 s27, s27, 0
	s_add_i32 s36, s39, s23
	global_load_lds_dwordx4 v[156:157], off
	v_lshl_add_u64 v[156:157], s[26:27], 0, v[162:163]
	s_mov_b32 m0, s36
	s_nop 0
	global_load_lds_dwordx4 v[156:157], off
	v_lshl_add_u64 v[156:157], s[26:27], 0, v[134:135]
	s_add_i32 m0, s36, 0x2000
	s_nop 0
	global_load_lds_dwordx4 v[156:157], off
	v_lshl_add_u64 v[156:157], v[234:235], 0, s[44:45]
	s_mov_b32 m0, s72
	s_nop 0
	global_load_lds_dwordx4 v[156:157], off
	v_lshl_add_u64 v[156:157], v[236:237], 0, s[44:45]
	s_mov_b32 m0, s73
	s_nop 0
	global_load_lds_dwordx4 v[156:157], off
	s_waitcnt vmcnt(8)
	s_waitcnt lgkmcnt(0)
	s_barrier
	v_mfma_i32_16x16x64_i8 v[62:65], v[144:147], v[198:201], v[62:65]
	v_mfma_i32_16x16x64_i8 v[54:57], v[152:155], v[198:201], v[54:57]
	v_mfma_i32_16x16x64_i8 v[46:49], v[144:147], v[206:209], v[46:49]
	v_mfma_i32_16x16x64_i8 v[38:41], v[152:155], v[206:209], v[38:41]
	v_mfma_i32_16x16x64_i8 v[30:33], v[144:147], v[214:217], v[30:33]
	v_mfma_i32_16x16x64_i8 v[22:25], v[152:155], v[214:217], v[22:25]
	v_mfma_i32_16x16x64_i8 v[14:17], v[144:147], v[226:229], v[14:17]
	v_mfma_i32_16x16x64_i8 v[6:9], v[152:155], v[226:229], v[6:9]
	v_mfma_i32_16x16x64_i8 v[62:65], v[148:151], v[202:205], v[62:65]
	v_mfma_i32_16x16x64_i8 v[54:57], v[178:181], v[202:205], v[54:57]
	v_mfma_i32_16x16x64_i8 v[46:49], v[148:151], v[210:213], v[46:49]
	v_mfma_i32_16x16x64_i8 v[38:41], v[178:181], v[210:213], v[38:41]
	v_mfma_i32_16x16x64_i8 v[30:33], v[148:151], v[222:225], v[30:33]
	v_mfma_i32_16x16x64_i8 v[22:25], v[178:181], v[222:225], v[22:25]
	v_mfma_i32_16x16x64_i8 v[14:17], v[148:151], v[230:233], v[14:17]
	v_mfma_i32_16x16x64_i8 v[6:9], v[178:181], v[230:233], v[6:9]
	v_mfma_i32_16x16x64_i8 v[58:61], v[182:185], v[198:201], v[58:61]
	v_mfma_i32_16x16x64_i8 v[50:53], v[190:193], v[198:201], v[50:53]
	v_mfma_i32_16x16x64_i8 v[42:45], v[182:185], v[206:209], v[42:45]
	v_mfma_i32_16x16x64_i8 v[34:37], v[190:193], v[206:209], v[34:37]
	v_mfma_i32_16x16x64_i8 v[26:29], v[182:185], v[214:217], v[26:29]
	v_mfma_i32_16x16x64_i8 v[18:21], v[190:193], v[214:217], v[18:21]
	v_mfma_i32_16x16x64_i8 v[10:13], v[182:185], v[226:229], v[10:13]
	v_mfma_i32_16x16x64_i8 v[2:5], v[190:193], v[226:229], v[2:5]
	v_mfma_i32_16x16x64_i8 v[58:61], v[186:189], v[202:205], v[58:61]
	v_mfma_i32_16x16x64_i8 v[50:53], v[194:197], v[202:205], v[50:53]
	v_mfma_i32_16x16x64_i8 v[42:45], v[186:189], v[210:213], v[42:45]
	v_mfma_i32_16x16x64_i8 v[34:37], v[194:197], v[210:213], v[34:37]
	v_mfma_i32_16x16x64_i8 v[26:29], v[186:189], v[222:225], v[26:29]
	v_mfma_i32_16x16x64_i8 v[18:21], v[194:197], v[222:225], v[18:21]
	v_mfma_i32_16x16x64_i8 v[10:13], v[186:189], v[230:233], v[10:13]
	v_mfma_i32_16x16x64_i8 v[2:5], v[194:197], v[230:233], v[2:5]
	s_barrier
	s_add_i32 s21, s21, 2
	s_add_u32 s13, s13, 0x100
	s_addc_u32 s15, s15, 0
	s_add_u32 s24, s24, 0x100
	s_addc_u32 s25, s25, 0
	s_cmp_gt_u32 s21, 13
	s_cbranch_scc0 .LBB0_323
	s_and_b64 vcc, exec, s[10:11]
	s_cbranch_vccz .LBB0_326
	s_barrier

.LBB0_329:
	s_mov_b32 s101, 1
	s_andn2_b64 vcc, exec, s[8:9]
	s_cbranch_vccnz .LBB0_312
	s_barrier
	s_branch .LBB0_312

.LBB0_1320:
	s_mov_b32 s101, 0
	s_and_b32 s13, s12, 3
	s_add_i32 m0, s69, 0x18000
	v_lshl_add_u64 v[8:9], v[8:9], 0, s[44:45]
	s_lshl_b32 s15, s10, 6
	s_lshl_b32 s16, s10, 13
	s_lshl_b32 s17, s13, 12
	s_waitcnt vmcnt(2)
	s_barrier
	global_load_lds_dwordx4 v[8:9], off
	v_lshl_add_u64 v[6:7], v[6:7], 0, s[44:45]
	s_add_i32 m0, s69, 0x1a000
	s_add_i32 s73, s69, 0x8000
	s_add_i32 s74, s69, 0xa000
	global_load_lds_dwordx4 v[6:7], off
	v_lshl_add_u64 v[2:3], v[2:3], 0, s[44:45]
	s_mov_b32 m0, s73
	s_add_u32 s10, s26, 0x80080
	global_load_lds_dwordx4 v[2:3], off
	v_lshl_add_u64 v[2:3], v[4:5], 0, s[44:45]
	s_mov_b32 m0, s74
	s_addc_u32 s11, s27, 0
	global_load_lds_dwordx4 v[2:3], off
	s_add_i32 m0, s69, 0x1c000
	v_lshl_add_u64 v[2:3], s[10:11], 0, v[162:163]
	global_load_lds_dwordx4 v[2:3], off
	v_lshl_add_u64 v[2:3], s[10:11], 0, v[134:135]
	s_add_i32 m0, s69, 0x1e000
	s_and_b32 s10, s2, 7
	global_load_lds_dwordx4 v[2:3], off
	s_lshl_b32 s11, s10, 3
	s_ashr_i32 s76, s2, 6
	s_bfe_u32 s78, s2, 0x30003
	s_mul_i32 s10, s10, 44
	s_ashr_i32 s75, s2, 31
	s_add_i32 s77, s11, s76
	s_or_b32 s79, s11, s78
	s_lshr_b32 s80, s10, 3
	v_lshrrev_b32_e32 v4, 1, v143
	s_cmpk_lt_u32 s14, 0x100
	v_and_b32_e32 v159, 24, v4
	s_cselect_b64 s[10:11], -1, 0
	s_bfe_u32 s81, s12, 0x10001
	s_lshl_b32 s12, s12, 6
	v_and_b32_e32 v3, 15, v143
	v_lshlrev_b32_e32 v4, 1, v159
	v_lshlrev_b32_e32 v5, 2, v143
	s_ashr_i32 s14, s15, 31
	s_lshl_b32 s82, s13, 7
	s_and_b32 s12, s12, 64
	v_or_b32_e32 v2, s15, v3
	v_lshl_or_b32 v3, v3, 6, v4
	v_and_b32_e32 v5, 32, v5
	s_add_u32 s4, s4, s12
	v_bitop3_b32 v6, v3, s16, v5 bitop3:0xde
	v_bitop3_b32 v161, v3, s17, v5 bitop3:0xde
	v_mov_b32_e32 v3, s14
	s_addc_u32 s5, s5, 0
	v_mov_b32_e32 v5, v163
	v_lshlrev_b32_e32 v173, 3, v2
	v_lshl_add_u64 v[4:5], s[4:5], 0, v[4:5]
	v_lshlrev_b64 v[2:3], 7, v[2:3]
	v_lshl_add_u64 v[2:3], v[4:5], 0, v[2:3]
	s_mov_b64 s[4:5], 0x58000000
	v_lshl_add_u64 v[136:137], v[2:3], 0, s[4:5]
	v_lshlrev_b32_e32 v2, 14, v13
	v_and_b32_e32 v2, 0xffff8000, v2
	v_lshl_add_u32 v2, v14, 11, v2
	v_and_b32_e32 v3, 1, v13
	v_lshl_or_b32 v2, v3, 6, v2
	v_lshl_add_u32 v138, v15, 1, v2
	v_lshlrev_b32_e32 v2, 14, v10
	v_and_b32_e32 v2, 0xffff8000, v2
	s_waitcnt vmcnt(6)
	v_lshl_add_u32 v2, v11, 11, v2
	v_and_b32_e32 v3, 1, v10
	v_lshl_or_b32 v2, v3, 6, v2
	v_mov_b32_e32 v139, v163
	v_lshl_add_u32 v140, v12, 1, v2
	v_mov_b32_e32 v141, v163
	s_mov_b32 s84, 0
	v_add_u32_e32 v177, 0, v6
	s_mov_b32 s83, 0
	s_barrier
	s_branch .LBB0_1323

.LBB0_1332:
	s_add_u32 s26, s24, 0xfffc0080
	s_addc_u32 s27, s25, -1
	s_add_i32 s36, 0, 0x10000
	s_cmp_eq_u32 s21, 12
	s_cselect_b32 s57, s17, s27
	s_cselect_b32 s56, s16, s26
	v_add_u32_e32 v142, s36, v161
	s_cselect_b32 s27, s19, s15
	s_cselect_b32 s26, s18, s13
	s_add_i32 s38, 0, 0x14000
	ds_read_b128 v[144:147], v142
	ds_read_b128 v[148:151], v142 offset:1024
	ds_read_b128 v[152:155], v142 offset:2048
	ds_read_b128 v[178:181], v142 offset:3072
	v_add_u32_e32 v142, s38, v161
	ds_read_b128 v[182:185], v142
	ds_read_b128 v[186:189], v142 offset:1024
	ds_read_b128 v[190:193], v142 offset:2048
	ds_read_b128 v[194:197], v142 offset:3072
	v_lshl_add_u64 v[156:157], s[24:25], 0, v[140:141]
	s_add_i32 m0, s69, 0xc000
	ds_read_b128 v[198:201], v177
	ds_read_b128 v[202:205], v177 offset:1024
	ds_read_b128 v[206:209], v177 offset:2048
	ds_read_b128 v[210:213], v177 offset:3072
	ds_read_b128 v[214:217], v177 offset:4096
	ds_read_b128 v[222:225], v177 offset:5120
	ds_read_b128 v[226:229], v177 offset:6144
	ds_read_b128 v[230:233], v177 offset:7168
	global_load_lds_dwordx4 v[156:157], off
	v_lshl_add_u64 v[156:157], s[24:25], 0, v[138:139]
	s_add_i32 m0, s69, 0xe000
	s_nop 0
	global_load_lds_dwordx4 v[156:157], off
	s_waitcnt vmcnt(18)
	s_cmp_eq_i32 s21, -2
	s_cselect_b32 s100, s101, 0
	s_cmp_lg_u32 s100, 0
	s_cbranch_scc1 .Lrw_skip1332_0
	s_waitcnt vmcnt(8)
.Lrw_skip1332_0:
	s_waitcnt lgkmcnt(0)
	s_barrier
	v_mfma_i32_16x16x64_i8 v[126:129], v[144:147], v[198:201], v[126:129]
	v_mfma_i32_16x16x64_i8 v[118:121], v[152:155], v[198:201], v[118:121]
	v_mfma_i32_16x16x64_i8 v[110:113], v[144:147], v[206:209], v[110:113]
	v_mfma_i32_16x16x64_i8 v[102:105], v[152:155], v[206:209], v[102:105]
	v_mfma_i32_16x16x64_i8 v[94:97], v[144:147], v[214:217], v[94:97]
	v_mfma_i32_16x16x64_i8 v[86:89], v[152:155], v[214:217], v[86:89]
	v_mfma_i32_16x16x64_i8 v[78:81], v[144:147], v[226:229], v[78:81]
	v_mfma_i32_16x16x64_i8 v[70:73], v[152:155], v[226:229], v[70:73]
	v_mfma_i32_16x16x64_i8 v[126:129], v[148:151], v[202:205], v[126:129]
	v_mfma_i32_16x16x64_i8 v[118:121], v[178:181], v[202:205], v[118:121]
	v_mfma_i32_16x16x64_i8 v[110:113], v[148:151], v[210:213], v[110:113]
	v_mfma_i32_16x16x64_i8 v[102:105], v[178:181], v[210:213], v[102:105]
	v_mfma_i32_16x16x64_i8 v[94:97], v[148:151], v[222:225], v[94:97]
	v_mfma_i32_16x16x64_i8 v[86:89], v[178:181], v[222:225], v[86:89]
	v_mfma_i32_16x16x64_i8 v[78:81], v[148:151], v[230:233], v[78:81]
	v_mfma_i32_16x16x64_i8 v[70:73], v[178:181], v[230:233], v[70:73]
	v_mfma_i32_16x16x64_i8 v[122:125], v[182:185], v[198:201], v[122:125]
	v_mfma_i32_16x16x64_i8 v[114:117], v[190:193], v[198:201], v[114:117]
	v_mfma_i32_16x16x64_i8 v[106:109], v[182:185], v[206:209], v[106:109]
	v_mfma_i32_16x16x64_i8 v[98:101], v[190:193], v[206:209], v[98:101]
	v_mfma_i32_16x16x64_i8 v[90:93], v[182:185], v[214:217], v[90:93]
	v_mfma_i32_16x16x64_i8 v[82:85], v[190:193], v[214:217], v[82:85]
	v_mfma_i32_16x16x64_i8 v[74:77], v[182:185], v[226:229], v[74:77]
	v_mfma_i32_16x16x64_i8 v[66:69], v[190:193], v[226:229], v[66:69]
	v_mfma_i32_16x16x64_i8 v[122:125], v[186:189], v[202:205], v[122:125]
	v_mfma_i32_16x16x64_i8 v[114:117], v[194:197], v[202:205], v[114:117]
	v_mfma_i32_16x16x64_i8 v[106:109], v[186:189], v[210:213], v[106:109]
	v_mfma_i32_16x16x64_i8 v[98:101], v[194:197], v[210:213], v[98:101]
	v_mfma_i32_16x16x64_i8 v[90:93], v[186:189], v[222:225], v[90:93]
	v_mfma_i32_16x16x64_i8 v[82:85], v[194:197], v[222:225], v[82:85]
	v_mfma_i32_16x16x64_i8 v[74:77], v[186:189], v[230:233], v[74:77]
	v_mfma_i32_16x16x64_i8 v[66:69], v[194:197], v[230:233], v[66:69]
	s_barrier
	s_add_i32 s36, s36, s23
	v_lshl_add_u64 v[156:157], s[26:27], 0, v[162:163]
	s_mov_b32 m0, s36
	ds_read_b128 v[198:201], v177 offset:16384
	ds_read_b128 v[202:205], v177 offset:17408
	ds_read_b128 v[206:209], v177 offset:18432
	ds_read_b128 v[210:213], v177 offset:19456
	ds_read_b128 v[214:217], v177 offset:20480
	ds_read_b128 v[222:225], v177 offset:21504
	ds_read_b128 v[226:229], v177 offset:22528
	ds_read_b128 v[230:233], v177 offset:23552
	global_load_lds_dwordx4 v[156:157], off
	s_add_i32 m0, s36, 0x2000
	s_add_u32 s36, s26, 0x80000
	v_lshl_add_u64 v[168:169], s[26:27], 0, v[134:135]
	s_addc_u32 s37, s27, 0
	s_add_i32 s38, s38, s23
	global_load_lds_dwordx4 v[168:169], off
	v_lshl_add_u64 v[170:171], s[36:37], 0, v[162:163]
	s_mov_b32 m0, s38
	v_lshl_add_u64 v[174:175], s[56:57], 0, v[132:133]
	global_load_lds_dwordx4 v[170:171], off
	v_lshl_add_u64 v[170:171], s[36:37], 0, v[134:135]
	s_add_i32 m0, s38, 0x2000
	s_nop 0
	global_load_lds_dwordx4 v[170:171], off
	v_lshl_add_u64 v[170:171], s[56:57], 0, v[130:131]
	s_mov_b32 m0, s69
	s_nop 0
	global_load_lds_dwordx4 v[170:171], off
	s_mov_b32 m0, s70
	s_nop 0
	global_load_lds_dwordx4 v[174:175], off
	s_waitcnt vmcnt(18)
	s_cmp_eq_i32 s21, -2
	s_cselect_b32 s100, s101, 0
	s_cmp_lg_u32 s100, 0
	s_cbranch_scc1 .Lrw_skip1332_1
	s_waitcnt vmcnt(8)
.Lrw_skip1332_1:
	s_waitcnt lgkmcnt(0)
	s_barrier
	v_mfma_i32_16x16x64_i8 v[62:65], v[144:147], v[198:201], v[62:65]
	v_mfma_i32_16x16x64_i8 v[54:57], v[152:155], v[198:201], v[54:57]
	v_mfma_i32_16x16x64_i8 v[46:49], v[144:147], v[206:209], v[46:49]
	v_mfma_i32_16x16x64_i8 v[38:41], v[152:155], v[206:209], v[38:41]
	v_mfma_i32_16x16x64_i8 v[30:33], v[144:147], v[214:217], v[30:33]
	v_mfma_i32_16x16x64_i8 v[22:25], v[152:155], v[214:217], v[22:25]
	v_mfma_i32_16x16x64_i8 v[14:17], v[144:147], v[226:229], v[14:17]
	v_mfma_i32_16x16x64_i8 v[6:9], v[152:155], v[226:229], v[6:9]
	v_mfma_i32_16x16x64_i8 v[62:65], v[148:151], v[202:205], v[62:65]
	v_mfma_i32_16x16x64_i8 v[54:57], v[178:181], v[202:205], v[54:57]
	v_mfma_i32_16x16x64_i8 v[46:49], v[148:151], v[210:213], v[46:49]
	v_mfma_i32_16x16x64_i8 v[38:41], v[178:181], v[210:213], v[38:41]
	v_mfma_i32_16x16x64_i8 v[30:33], v[148:151], v[222:225], v[30:33]
	v_mfma_i32_16x16x64_i8 v[22:25], v[178:181], v[222:225], v[22:25]
	v_mfma_i32_16x16x64_i8 v[14:17], v[148:151], v[230:233], v[14:17]
	v_mfma_i32_16x16x64_i8 v[6:9], v[178:181], v[230:233], v[6:9]
	v_mfma_i32_16x16x64_i8 v[58:61], v[182:185], v[198:201], v[58:61]
	v_mfma_i32_16x16x64_i8 v[50:53], v[190:193], v[198:201], v[50:53]
	v_mfma_i32_16x16x64_i8 v[42:45], v[182:185], v[206:209], v[42:45]
	v_mfma_i32_16x16x64_i8 v[34:37], v[190:193], v[206:209], v[34:37]
	v_mfma_i32_16x16x64_i8 v[26:29], v[182:185], v[214:217], v[26:29]
	v_mfma_i32_16x16x64_i8 v[18:21], v[190:193], v[214:217], v[18:21]
	v_mfma_i32_16x16x64_i8 v[10:13], v[182:185], v[226:229], v[10:13]
	v_mfma_i32_16x16x64_i8 v[2:5], v[190:193], v[226:229], v[2:5]
	v_mfma_i32_16x16x64_i8 v[58:61], v[186:189], v[202:205], v[58:61]
	v_mfma_i32_16x16x64_i8 v[50:53], v[194:197], v[202:205], v[50:53]
	v_mfma_i32_16x16x64_i8 v[42:45], v[186:189], v[210:213], v[42:45]
	v_mfma_i32_16x16x64_i8 v[34:37], v[194:197], v[210:213], v[34:37]
	v_mfma_i32_16x16x64_i8 v[26:29], v[186:189], v[222:225], v[26:29]
	v_mfma_i32_16x16x64_i8 v[18:21], v[194:197], v[222:225], v[18:21]
	v_mfma_i32_16x16x64_i8 v[10:13], v[186:189], v[230:233], v[10:13]
	v_mfma_i32_16x16x64_i8 v[2:5], v[194:197], v[230:233], v[2:5]
	s_barrier
	s_add_i32 s38, 0, 0x18000
	v_add_u32_e32 v142, s38, v161
	s_add_i32 s39, 0, 0x1c000
	ds_read_b128 v[144:147], v142
	ds_read_b128 v[148:151], v142 offset:1024
	ds_read_b128 v[152:155], v142 offset:2048
	ds_read_b128 v[178:181], v142 offset:3072
	v_add_u32_e32 v142, s39, v161
	ds_read_b128 v[182:185], v142
	ds_read_b128 v[186:189], v142 offset:1024
	ds_read_b128 v[190:193], v142 offset:2048
	ds_read_b128 v[194:197], v142 offset:3072
	s_add_u32 s36, s56, 0x40000
	s_addc_u32 s37, s57, 0
	s_mov_b32 m0, s71
	v_lshl_add_u64 v[234:235], s[36:37], 0, v[130:131]
	ds_read_b128 v[198:201], v177 offset:32768
	ds_read_b128 v[202:205], v177 offset:33792
	ds_read_b128 v[206:209], v177 offset:34816
	ds_read_b128 v[210:213], v177 offset:35840
	ds_read_b128 v[214:217], v177 offset:36864
	ds_read_b128 v[222:225], v177 offset:37888
	ds_read_b128 v[226:229], v177 offset:38912
	ds_read_b128 v[230:233], v177 offset:39936
	global_load_lds_dwordx4 v[234:235], off
	v_lshl_add_u64 v[234:235], s[36:37], 0, v[132:133]
	s_mov_b32 m0, s72
	s_nop 0
	global_load_lds_dwordx4 v[234:235], off
	s_waitcnt vmcnt(8)
	s_waitcnt lgkmcnt(0)
	s_barrier
	v_mfma_i32_16x16x64_i8 v[126:129], v[144:147], v[198:201], v[126:129]
	v_mfma_i32_16x16x64_i8 v[118:121], v[152:155], v[198:201], v[118:121]
	v_mfma_i32_16x16x64_i8 v[110:113], v[144:147], v[206:209], v[110:113]
	v_mfma_i32_16x16x64_i8 v[102:105], v[152:155], v[206:209], v[102:105]
	v_mfma_i32_16x16x64_i8 v[94:97], v[144:147], v[214:217], v[94:97]
	v_mfma_i32_16x16x64_i8 v[86:89], v[152:155], v[214:217], v[86:89]
	v_mfma_i32_16x16x64_i8 v[78:81], v[144:147], v[226:229], v[78:81]
	v_mfma_i32_16x16x64_i8 v[70:73], v[152:155], v[226:229], v[70:73]
	v_mfma_i32_16x16x64_i8 v[126:129], v[148:151], v[202:205], v[126:129]
	v_mfma_i32_16x16x64_i8 v[118:121], v[178:181], v[202:205], v[118:121]
	v_mfma_i32_16x16x64_i8 v[110:113], v[148:151], v[210:213], v[110:113]
	v_mfma_i32_16x16x64_i8 v[102:105], v[178:181], v[210:213], v[102:105]
	v_mfma_i32_16x16x64_i8 v[94:97], v[148:151], v[222:225], v[94:97]
	v_mfma_i32_16x16x64_i8 v[86:89], v[178:181], v[222:225], v[86:89]
	v_mfma_i32_16x16x64_i8 v[78:81], v[148:151], v[230:233], v[78:81]
	v_mfma_i32_16x16x64_i8 v[70:73], v[178:181], v[230:233], v[70:73]
	v_mfma_i32_16x16x64_i8 v[122:125], v[182:185], v[198:201], v[122:125]
	v_mfma_i32_16x16x64_i8 v[114:117], v[190:193], v[198:201], v[114:117]
	v_mfma_i32_16x16x64_i8 v[106:109], v[182:185], v[206:209], v[106:109]
	v_mfma_i32_16x16x64_i8 v[98:101], v[190:193], v[206:209], v[98:101]
	v_mfma_i32_16x16x64_i8 v[90:93], v[182:185], v[214:217], v[90:93]
	v_mfma_i32_16x16x64_i8 v[82:85], v[190:193], v[214:217], v[82:85]
	v_mfma_i32_16x16x64_i8 v[74:77], v[182:185], v[226:229], v[74:77]
	v_mfma_i32_16x16x64_i8 v[66:69], v[190:193], v[226:229], v[66:69]
	v_mfma_i32_16x16x64_i8 v[122:125], v[186:189], v[202:205], v[122:125]
	v_mfma_i32_16x16x64_i8 v[114:117], v[194:197], v[202:205], v[114:117]
	v_mfma_i32_16x16x64_i8 v[106:109], v[186:189], v[210:213], v[106:109]
	v_mfma_i32_16x16x64_i8 v[98:101], v[194:197], v[210:213], v[98:101]
	v_mfma_i32_16x16x64_i8 v[90:93], v[186:189], v[222:225], v[90:93]
	v_mfma_i32_16x16x64_i8 v[82:85], v[194:197], v[222:225], v[82:85]
	v_mfma_i32_16x16x64_i8 v[74:77], v[186:189], v[230:233], v[74:77]
	v_mfma_i32_16x16x64_i8 v[66:69], v[194:197], v[230:233], v[66:69]
	s_barrier
	s_add_i32 s36, s38, s23
	v_lshl_add_u64 v[156:157], v[156:157], 0, s[44:45]
	s_mov_b32 m0, s36
	ds_read_b128 v[198:201], v177 offset:49152
	ds_read_b128 v[202:205], v177 offset:50176
	ds_read_b128 v[206:209], v177 offset:51200
	ds_read_b128 v[210:213], v177 offset:52224
	ds_read_b128 v[214:217], v177 offset:53248
	ds_read_b128 v[222:225], v177 offset:54272
	ds_read_b128 v[226:229], v177 offset:55296
	ds_read_b128 v[230:233], v177 offset:56320
	global_load_lds_dwordx4 v[156:157], off
	s_add_i32 m0, s36, 0x2000
	s_add_u32 s26, s26, 0x80080
	v_lshl_add_u64 v[156:157], v[168:169], 0, s[44:45]
	s_addc_u32 s27, s27, 0
	s_add_i32 s36, s39, s23
	global_load_lds_dwordx4 v[156:157], off
	v_lshl_add_u64 v[156:157], s[26:27], 0, v[162:163]
	s_mov_b32 m0, s36
	s_nop 0
	global_load_lds_dwordx4 v[156:157], off
	v_lshl_add_u64 v[156:157], s[26:27], 0, v[134:135]
	s_add_i32 m0, s36, 0x2000
	s_nop 0
	global_load_lds_dwordx4 v[156:157], off
	v_lshl_add_u64 v[156:157], v[170:171], 0, s[44:45]
	s_mov_b32 m0, s73
	s_nop 0
	global_load_lds_dwordx4 v[156:157], off
	v_lshl_add_u64 v[156:157], v[174:175], 0, s[44:45]
	s_mov_b32 m0, s74
	s_nop 0
	global_load_lds_dwordx4 v[156:157], off
	s_waitcnt vmcnt(8)
	s_waitcnt lgkmcnt(0)
	s_barrier
	v_mfma_i32_16x16x64_i8 v[62:65], v[144:147], v[198:201], v[62:65]
	v_mfma_i32_16x16x64_i8 v[54:57], v[152:155], v[198:201], v[54:57]
	v_mfma_i32_16x16x64_i8 v[46:49], v[144:147], v[206:209], v[46:49]
	v_mfma_i32_16x16x64_i8 v[38:41], v[152:155], v[206:209], v[38:41]
	v_mfma_i32_16x16x64_i8 v[30:33], v[144:147], v[214:217], v[30:33]
	v_mfma_i32_16x16x64_i8 v[22:25], v[152:155], v[214:217], v[22:25]
	v_mfma_i32_16x16x64_i8 v[14:17], v[144:147], v[226:229], v[14:17]
	v_mfma_i32_16x16x64_i8 v[6:9], v[152:155], v[226:229], v[6:9]
	v_mfma_i32_16x16x64_i8 v[62:65], v[148:151], v[202:205], v[62:65]
	v_mfma_i32_16x16x64_i8 v[54:57], v[178:181], v[202:205], v[54:57]
	v_mfma_i32_16x16x64_i8 v[46:49], v[148:151], v[210:213], v[46:49]
	v_mfma_i32_16x16x64_i8 v[38:41], v[178:181], v[210:213], v[38:41]
	v_mfma_i32_16x16x64_i8 v[30:33], v[148:151], v[222:225], v[30:33]
	v_mfma_i32_16x16x64_i8 v[22:25], v[178:181], v[222:225], v[22:25]
	v_mfma_i32_16x16x64_i8 v[14:17], v[148:151], v[230:233], v[14:17]
	v_mfma_i32_16x16x64_i8 v[6:9], v[178:181], v[230:233], v[6:9]
	v_mfma_i32_16x16x64_i8 v[58:61], v[182:185], v[198:201], v[58:61]
	v_mfma_i32_16x16x64_i8 v[50:53], v[190:193], v[198:201], v[50:53]
	v_mfma_i32_16x16x64_i8 v[42:45], v[182:185], v[206:209], v[42:45]
	v_mfma_i32_16x16x64_i8 v[34:37], v[190:193], v[206:209], v[34:37]
	v_mfma_i32_16x16x64_i8 v[26:29], v[182:185], v[214:217], v[26:29]
	v_mfma_i32_16x16x64_i8 v[18:21], v[190:193], v[214:217], v[18:21]
	v_mfma_i32_16x16x64_i8 v[10:13], v[182:185], v[226:229], v[10:13]
	v_mfma_i32_16x16x64_i8 v[2:5], v[190:193], v[226:229], v[2:5]
	v_mfma_i32_16x16x64_i8 v[58:61], v[186:189], v[202:205], v[58:61]
	v_mfma_i32_16x16x64_i8 v[50:53], v[194:197], v[202:205], v[50:53]
	v_mfma_i32_16x16x64_i8 v[42:45], v[186:189], v[210:213], v[42:45]
	v_mfma_i32_16x16x64_i8 v[34:37], v[194:197], v[210:213], v[34:37]
	v_mfma_i32_16x16x64_i8 v[26:29], v[186:189], v[222:225], v[26:29]
	v_mfma_i32_16x16x64_i8 v[18:21], v[194:197], v[222:225], v[18:21]
	v_mfma_i32_16x16x64_i8 v[10:13], v[186:189], v[230:233], v[10:13]
	v_mfma_i32_16x16x64_i8 v[2:5], v[194:197], v[230:233], v[2:5]
	s_barrier
	s_add_i32 s21, s21, 2
	s_add_u32 s13, s13, 0x100
	s_addc_u32 s15, s15, 0
	s_add_u32 s24, s24, 0x100
	s_addc_u32 s25, s25, 0
	s_cmp_gt_u32 s21, 13
	s_cbranch_scc0 .LBB0_1332
	s_and_b64 vcc, exec, s[10:11]
	s_cbranch_vccz .LBB0_1335
	s_barrier
